# v135 with the beta/alpha GEMV operand loads running 8 K-blocks ahead instead of 4
# speedup vs baseline: 1.0033x; 1.0009x over previous
; __device__ __forceinline__ float bf2f(bfu h) { return __uint_as_float(((unsigned)h) << 16); }
; #define SHX(v, m) shx_((v), (m), lane)
; __device__ __forceinline__ int ptid_(int wave) { int l_; asm volatile("v_mbcnt_lo_u32_b32 %0, -1, 0\n\tv_mbcnt_hi_u32_b32 %0, -1, %0" : "=v"(l_)); return (wave << 6) | l_; }
; __device__ void ba_item(const Params& p, int L, int rp) {
;     ...
;   int tid = ptid_(p.tid); asm volatile("" : "+v"(tid));
;   const int wid = tid >> 6, lane = tid & 63;
;   f32x4 wr_[8][4];
;   _Pragma("unroll") for (int j = 0; j < 8; ++j) _Pragma("unroll") for (int e4 = 0; e4 < 4; ++e4)
;     wr_[j][e4] = *(const f32x4*)(wba + j * 1024 + lane * 16 + e4 * 4);
;   for (int bt = 0; bt < 8; ++bt) {
;     bf16x8 h0[2], h1[2]; f32x4 ps[2][4];
;     _Pragma("unroll") for (int u = 0; u < 2; ++u) {
;       const int row = rp * 128 + wid * 16 + bt * 2 + u;
;       const bfu* hr = hb + (long)row * 1024 + lane * 16;
;       h0[u] = *(const bf16x8*)hr; h1[u] = *(const bf16x8*)(hr + 8);
;       _Pragma("unroll") for (int i = 0; i < 4; ++i) ps[u][i] = *(const f32x4*)(rowss + (long)row * 16 + i * 4);
;     }
;     _Pragma("unroll") for (int u = 0; u < 2; ++u) {
;       const int row = rp * 128 + wid * 16 + bt * 2 + u;
;       float hf[16];
;       _Pragma("unroll") for (int e = 0; e < 8; ++e) { hf[e] = bf2f((bfu)h0[u][e]); hf[8 + e] = bf2f((bfu)h1[u][e]); }
;       float a[8];
;       _Pragma("unroll") for (int j = 0; j < 8; ++j) {
;         float s = 0.f;
;         _Pragma("unroll") for (int e4 = 0; e4 < 4; ++e4) _Pragma("unroll") for (int e = 0; e < 4; ++e) s += hf[e4 * 4 + e] * wr_[j][e4][e];
;         _Pragma("unroll") for (int o = 32; o >= 1; o >>= 1) s += SHX(s, o);
.LBB0_612:
	s_cmpk_gt_i32 s18, 0x6ff
	s_mov_b64 s[0:1], -1
	s_cbranch_scc0 .LBB0_628
	v_mbcnt_lo_u32_b32 v0, -1, 0
	v_mbcnt_hi_u32_b32 v0, -1, v0
	s_waitcnt vmcnt(0)
	v_readlane_b32 s24, v254, 62
	v_readlane_b32 s25, v254, 63
	s_lshr_b32 s2, s33, 2
	s_add_i32 s2, s2, s20
	s_add_i32 s2, s2, 0xfffc8000
	v_and_b32_e32 v2, 15, v0
	v_lshrrev_b32_e32 v3, 4, v0
	v_add_u32_e32 v192, s2, v2
	v_lshlrev_b32_e32 v192, 11, v192
	v_lshl_add_u32 v192, v3, 4, v192
	v_mov_b32_e32 v193, 0
	v_lshl_add_u64 v[4:5], s[80:81], 0, v[192:193]
	v_and_b32_e32 v192, 7, v2
	v_lshlrev_b32_e32 v192, 12, v192
	v_lshl_add_u32 v192, v3, 5, v192
	v_lshl_add_u64 v[6:7], s[26:27], 0, v[192:193]
	v_lshl_add_u32 v192, v3, 2, s2
	v_lshlrev_b32_e32 v192, 6, v192
	v_lshl_add_u64 v[184:185], s[24:25], 0, v[192:193]
	v_and_b32_e32 v186, 7, v2
	v_max_u32_e32 v192, 4, v186
	v_add_u32_e32 v192, s19, v192
	v_lshlrev_b32_e32 v192, 2, v192
	v_readlane_b32 s92, v254, 0
	v_readlane_b32 s93, v254, 1
	v_readlane_b32 s94, v254, 2
	v_readlane_b32 s95, v254, 3
	v_readlane_b32 s0, v252, 18
	v_readlane_b32 s1, v252, 19
	v_lshl_add_u32 v194, v3, 2, s2
	v_lshlrev_b32_e32 v194, 5, v194
	v_lshl_add_u32 v194, v186, 2, v194
	v_mov_b32_e32 v195, 0
	v_lshl_add_u64 v[188:189], s[0:1], 0, v[194:195]
	global_load_dword v190, v192, s[94:95]
	global_load_dword v191, v192, s[92:93]
	global_load_dwordx4 v[120:123], v[184:185], off offset:0
	global_load_dwordx4 v[124:127], v[184:185], off offset:16
	global_load_dwordx4 v[128:131], v[184:185], off offset:32
	global_load_dwordx4 v[132:135], v[184:185], off offset:48
	global_load_dwordx4 v[136:139], v[184:185], off offset:64
	global_load_dwordx4 v[140:143], v[184:185], off offset:80
	global_load_dwordx4 v[144:147], v[184:185], off offset:96
	global_load_dwordx4 v[148:151], v[184:185], off offset:112
	global_load_dwordx4 v[152:155], v[184:185], off offset:128
	global_load_dwordx4 v[156:159], v[184:185], off offset:144
	global_load_dwordx4 v[160:163], v[184:185], off offset:160
	global_load_dwordx4 v[164:167], v[184:185], off offset:176
	global_load_dwordx4 v[168:171], v[184:185], off offset:192
	global_load_dwordx4 v[172:175], v[184:185], off offset:208
	global_load_dwordx4 v[176:179], v[184:185], off offset:224
	global_load_dwordx4 v[180:183], v[184:185], off offset:240
	v_mov_b32_e32 v8, 0
	v_mov_b32_e32 v9, 0
	v_mov_b32_e32 v10, 0
	v_mov_b32_e32 v11, 0
	global_load_dwordx4 v[16:19], v[4:5], off
	global_load_dwordx4 v[20:23], v[6:7], off
	global_load_dwordx4 v[24:27], v[6:7], off offset:16
	global_load_dwordx4 v[28:31], v[4:5], off offset:64
	global_load_dwordx4 v[32:35], v[6:7], off offset:128
	global_load_dwordx4 v[36:39], v[6:7], off offset:144
	global_load_dwordx4 v[40:43], v[4:5], off offset:128
	global_load_dwordx4 v[44:47], v[6:7], off offset:256
	global_load_dwordx4 v[48:51], v[6:7], off offset:272
	global_load_dwordx4 v[52:55], v[4:5], off offset:192
	global_load_dwordx4 v[56:59], v[6:7], off offset:384
	global_load_dwordx4 v[60:63], v[6:7], off offset:400
	global_load_dwordx4 v[64:67], v[4:5], off offset:256
	global_load_dwordx4 v[68:71], v[6:7], off offset:512
	global_load_dwordx4 v[72:75], v[6:7], off offset:528
	global_load_dwordx4 v[76:79], v[4:5], off offset:320
	global_load_dwordx4 v[80:83], v[6:7], off offset:640
	global_load_dwordx4 v[84:87], v[6:7], off offset:656
	global_load_dwordx4 v[88:91], v[4:5], off offset:384
	global_load_dwordx4 v[92:95], v[6:7], off offset:768
	global_load_dwordx4 v[96:99], v[6:7], off offset:784
	global_load_dwordx4 v[100:103], v[4:5], off offset:448
	global_load_dwordx4 v[104:107], v[6:7], off offset:896
	global_load_dwordx4 v[108:111], v[6:7], off offset:912
	s_waitcnt vmcnt(21)
	v_lshlrev_b32_e32 v112, 16, v16
	v_and_b32_e32 v113, 0xffff0000, v16
	v_lshlrev_b32_e32 v114, 16, v17
	v_and_b32_e32 v115, 0xffff0000, v17
	v_lshlrev_b32_e32 v116, 16, v18
	v_and_b32_e32 v117, 0xffff0000, v18
	v_lshlrev_b32_e32 v118, 16, v19
	v_and_b32_e32 v119, 0xffff0000, v19
	v_mfma_f32_16x16x4_f32 v[8:11], v112, v20, v[8:11]
	v_mfma_f32_16x16x4_f32 v[8:11], v113, v21, v[8:11]
	v_mfma_f32_16x16x4_f32 v[8:11], v114, v22, v[8:11]
	v_mfma_f32_16x16x4_f32 v[8:11], v115, v23, v[8:11]
	v_mfma_f32_16x16x4_f32 v[8:11], v116, v24, v[8:11]
	v_mfma_f32_16x16x4_f32 v[8:11], v117, v25, v[8:11]
	v_mfma_f32_16x16x4_f32 v[8:11], v118, v26, v[8:11]
	v_mfma_f32_16x16x4_f32 v[8:11], v119, v27, v[8:11]
	global_load_dwordx4 v[16:19], v[4:5], off offset:512
	global_load_dwordx4 v[20:23], v[6:7], off offset:1024
	global_load_dwordx4 v[24:27], v[6:7], off offset:1040
	s_waitcnt vmcnt(21)
	v_lshlrev_b32_e32 v112, 16, v28
	v_and_b32_e32 v113, 0xffff0000, v28
	v_lshlrev_b32_e32 v114, 16, v29
	v_and_b32_e32 v115, 0xffff0000, v29
	v_lshlrev_b32_e32 v116, 16, v30
	v_and_b32_e32 v117, 0xffff0000, v30
	v_lshlrev_b32_e32 v118, 16, v31
	v_and_b32_e32 v119, 0xffff0000, v31
	v_mfma_f32_16x16x4_f32 v[8:11], v112, v32, v[8:11]
	v_mfma_f32_16x16x4_f32 v[8:11], v113, v33, v[8:11]
	v_mfma_f32_16x16x4_f32 v[8:11], v114, v34, v[8:11]
	v_mfma_f32_16x16x4_f32 v[8:11], v115, v35, v[8:11]
	v_mfma_f32_16x16x4_f32 v[8:11], v116, v36, v[8:11]
	v_mfma_f32_16x16x4_f32 v[8:11], v117, v37, v[8:11]
	v_mfma_f32_16x16x4_f32 v[8:11], v118, v38, v[8:11]
	v_mfma_f32_16x16x4_f32 v[8:11], v119, v39, v[8:11]
	global_load_dwordx4 v[28:31], v[4:5], off offset:576
	global_load_dwordx4 v[32:35], v[6:7], off offset:1152
	global_load_dwordx4 v[36:39], v[6:7], off offset:1168
	s_waitcnt vmcnt(21)
; #define SHX(v, m) shx_((v), (m), lane)
; __device__ void ba_item(const Params& p, int L, int rp) {
;     ...
;       _Pragma("unroll") for (int j = 0; j < 8; ++j) {
;         float s = 0.f;
;         _Pragma("unroll") for (int e4 = 0; e4 < 4; ++e4) _Pragma("unroll") for (int e = 0; e < 4; ++e) s += hf[e4 * 4 + e] * wr_[j][e4][e];
;         _Pragma("unroll") for (int o = 32; o >= 1; o >>= 1) s += SHX(s, o);
	v_lshlrev_b32_e32 v112, 16, v40
	v_and_b32_e32 v113, 0xffff0000, v40
	v_lshlrev_b32_e32 v114, 16, v41
	v_and_b32_e32 v115, 0xffff0000, v41
	v_lshlrev_b32_e32 v116, 16, v42
	v_and_b32_e32 v117, 0xffff0000, v42
	v_lshlrev_b32_e32 v118, 16, v43
	v_and_b32_e32 v119, 0xffff0000, v43
	v_mfma_f32_16x16x4_f32 v[8:11], v112, v44, v[8:11]
	v_mfma_f32_16x16x4_f32 v[8:11], v113, v45, v[8:11]
	v_mfma_f32_16x16x4_f32 v[8:11], v114, v46, v[8:11]
	v_mfma_f32_16x16x4_f32 v[8:11], v115, v47, v[8:11]
	v_mfma_f32_16x16x4_f32 v[8:11], v116, v48, v[8:11]
	v_mfma_f32_16x16x4_f32 v[8:11], v117, v49, v[8:11]
	v_mfma_f32_16x16x4_f32 v[8:11], v118, v50, v[8:11]
	v_mfma_f32_16x16x4_f32 v[8:11], v119, v51, v[8:11]
	global_load_dwordx4 v[40:43], v[4:5], off offset:640
	global_load_dwordx4 v[44:47], v[6:7], off offset:1280
	global_load_dwordx4 v[48:51], v[6:7], off offset:1296
	s_waitcnt vmcnt(21)
	v_lshlrev_b32_e32 v112, 16, v52
	v_and_b32_e32 v113, 0xffff0000, v52
	v_lshlrev_b32_e32 v114, 16, v53
	v_and_b32_e32 v115, 0xffff0000, v53
	v_lshlrev_b32_e32 v116, 16, v54
	v_and_b32_e32 v117, 0xffff0000, v54
	v_lshlrev_b32_e32 v118, 16, v55
	v_and_b32_e32 v119, 0xffff0000, v55
	v_mfma_f32_16x16x4_f32 v[8:11], v112, v56, v[8:11]
	v_mfma_f32_16x16x4_f32 v[8:11], v113, v57, v[8:11]
	v_mfma_f32_16x16x4_f32 v[8:11], v114, v58, v[8:11]
	v_mfma_f32_16x16x4_f32 v[8:11], v115, v59, v[8:11]
	v_mfma_f32_16x16x4_f32 v[8:11], v116, v60, v[8:11]
	v_mfma_f32_16x16x4_f32 v[8:11], v117, v61, v[8:11]
	v_mfma_f32_16x16x4_f32 v[8:11], v118, v62, v[8:11]
	v_mfma_f32_16x16x4_f32 v[8:11], v119, v63, v[8:11]
	global_load_dwordx4 v[52:55], v[4:5], off offset:704
	global_load_dwordx4 v[56:59], v[6:7], off offset:1408
	global_load_dwordx4 v[60:63], v[6:7], off offset:1424
	s_waitcnt vmcnt(21)
	v_lshlrev_b32_e32 v112, 16, v64
	v_and_b32_e32 v113, 0xffff0000, v64
	v_lshlrev_b32_e32 v114, 16, v65
	v_and_b32_e32 v115, 0xffff0000, v65
	v_lshlrev_b32_e32 v116, 16, v66
	v_and_b32_e32 v117, 0xffff0000, v66
	v_lshlrev_b32_e32 v118, 16, v67
	v_and_b32_e32 v119, 0xffff0000, v67
	v_mfma_f32_16x16x4_f32 v[8:11], v112, v68, v[8:11]
	v_mfma_f32_16x16x4_f32 v[8:11], v113, v69, v[8:11]
	v_mfma_f32_16x16x4_f32 v[8:11], v114, v70, v[8:11]
	v_mfma_f32_16x16x4_f32 v[8:11], v115, v71, v[8:11]
	v_mfma_f32_16x16x4_f32 v[8:11], v116, v72, v[8:11]
	v_mfma_f32_16x16x4_f32 v[8:11], v117, v73, v[8:11]
	v_mfma_f32_16x16x4_f32 v[8:11], v118, v74, v[8:11]
	v_mfma_f32_16x16x4_f32 v[8:11], v119, v75, v[8:11]
	global_load_dwordx4 v[64:67], v[4:5], off offset:768
	global_load_dwordx4 v[68:71], v[6:7], off offset:1536
	global_load_dwordx4 v[72:75], v[6:7], off offset:1552
	s_waitcnt vmcnt(21)
	v_lshlrev_b32_e32 v112, 16, v76
	v_and_b32_e32 v113, 0xffff0000, v76
	v_lshlrev_b32_e32 v114, 16, v77
	v_and_b32_e32 v115, 0xffff0000, v77
	v_lshlrev_b32_e32 v116, 16, v78
	v_and_b32_e32 v117, 0xffff0000, v78
	v_lshlrev_b32_e32 v118, 16, v79
	v_and_b32_e32 v119, 0xffff0000, v79
	v_mfma_f32_16x16x4_f32 v[8:11], v112, v80, v[8:11]
	v_mfma_f32_16x16x4_f32 v[8:11], v113, v81, v[8:11]
	v_mfma_f32_16x16x4_f32 v[8:11], v114, v82, v[8:11]
	v_mfma_f32_16x16x4_f32 v[8:11], v115, v83, v[8:11]
	v_mfma_f32_16x16x4_f32 v[8:11], v116, v84, v[8:11]
	v_mfma_f32_16x16x4_f32 v[8:11], v117, v85, v[8:11]
	v_mfma_f32_16x16x4_f32 v[8:11], v118, v86, v[8:11]
	v_mfma_f32_16x16x4_f32 v[8:11], v119, v87, v[8:11]
	global_load_dwordx4 v[76:79], v[4:5], off offset:832
	global_load_dwordx4 v[80:83], v[6:7], off offset:1664
	global_load_dwordx4 v[84:87], v[6:7], off offset:1680
	s_waitcnt vmcnt(21)
	v_lshlrev_b32_e32 v112, 16, v88
	v_and_b32_e32 v113, 0xffff0000, v88
	v_lshlrev_b32_e32 v114, 16, v89
	v_and_b32_e32 v115, 0xffff0000, v89
	v_lshlrev_b32_e32 v116, 16, v90
	v_and_b32_e32 v117, 0xffff0000, v90
	v_lshlrev_b32_e32 v118, 16, v91
	v_and_b32_e32 v119, 0xffff0000, v91
	v_mfma_f32_16x16x4_f32 v[8:11], v112, v92, v[8:11]
	v_mfma_f32_16x16x4_f32 v[8:11], v113, v93, v[8:11]
	v_mfma_f32_16x16x4_f32 v[8:11], v114, v94, v[8:11]
	v_mfma_f32_16x16x4_f32 v[8:11], v115, v95, v[8:11]
	v_mfma_f32_16x16x4_f32 v[8:11], v116, v96, v[8:11]
	v_mfma_f32_16x16x4_f32 v[8:11], v117, v97, v[8:11]
	v_mfma_f32_16x16x4_f32 v[8:11], v118, v98, v[8:11]
	v_mfma_f32_16x16x4_f32 v[8:11], v119, v99, v[8:11]
	global_load_dwordx4 v[88:91], v[4:5], off offset:896
	global_load_dwordx4 v[92:95], v[6:7], off offset:1792
	global_load_dwordx4 v[96:99], v[6:7], off offset:1808
	s_waitcnt vmcnt(21)
	v_lshlrev_b32_e32 v112, 16, v100
	v_and_b32_e32 v113, 0xffff0000, v100
	v_lshlrev_b32_e32 v114, 16, v101
	v_and_b32_e32 v115, 0xffff0000, v101
	v_lshlrev_b32_e32 v116, 16, v102
	v_and_b32_e32 v117, 0xffff0000, v102
	v_lshlrev_b32_e32 v118, 16, v103
	v_and_b32_e32 v119, 0xffff0000, v103
	v_mfma_f32_16x16x4_f32 v[8:11], v112, v104, v[8:11]
	v_mfma_f32_16x16x4_f32 v[8:11], v113, v105, v[8:11]
	v_mfma_f32_16x16x4_f32 v[8:11], v114, v106, v[8:11]
	v_mfma_f32_16x16x4_f32 v[8:11], v115, v107, v[8:11]
	v_mfma_f32_16x16x4_f32 v[8:11], v116, v108, v[8:11]
	v_mfma_f32_16x16x4_f32 v[8:11], v117, v109, v[8:11]
	v_mfma_f32_16x16x4_f32 v[8:11], v118, v110, v[8:11]
	v_mfma_f32_16x16x4_f32 v[8:11], v119, v111, v[8:11]
	global_load_dwordx4 v[100:103], v[4:5], off offset:960
	global_load_dwordx4 v[104:107], v[6:7], off offset:1920
	global_load_dwordx4 v[108:111], v[6:7], off offset:1936
	s_waitcnt vmcnt(21)
; #define SHX(v, m) shx_((v), (m), lane)
; __device__ void ba_item(const Params& p, int L, int rp) {
;     ...
;       _Pragma("unroll") for (int j = 0; j < 8; ++j) {
;         float s = 0.f;
;         _Pragma("unroll") for (int e4 = 0; e4 < 4; ++e4) _Pragma("unroll") for (int e = 0; e < 4; ++e) s += hf[e4 * 4 + e] * wr_[j][e4][e];
;         _Pragma("unroll") for (int o = 32; o >= 1; o >>= 1) s += SHX(s, o);
	v_lshlrev_b32_e32 v112, 16, v16
	v_and_b32_e32 v113, 0xffff0000, v16
	v_lshlrev_b32_e32 v114, 16, v17
	v_and_b32_e32 v115, 0xffff0000, v17
	v_lshlrev_b32_e32 v116, 16, v18
	v_and_b32_e32 v117, 0xffff0000, v18
	v_lshlrev_b32_e32 v118, 16, v19
	v_and_b32_e32 v119, 0xffff0000, v19
	v_mfma_f32_16x16x4_f32 v[8:11], v112, v20, v[8:11]
	v_mfma_f32_16x16x4_f32 v[8:11], v113, v21, v[8:11]
	v_mfma_f32_16x16x4_f32 v[8:11], v114, v22, v[8:11]
	v_mfma_f32_16x16x4_f32 v[8:11], v115, v23, v[8:11]
	v_mfma_f32_16x16x4_f32 v[8:11], v116, v24, v[8:11]
	v_mfma_f32_16x16x4_f32 v[8:11], v117, v25, v[8:11]
	v_mfma_f32_16x16x4_f32 v[8:11], v118, v26, v[8:11]
	v_mfma_f32_16x16x4_f32 v[8:11], v119, v27, v[8:11]
	global_load_dwordx4 v[16:19], v[4:5], off offset:1024
	global_load_dwordx4 v[20:23], v[6:7], off offset:2048
	global_load_dwordx4 v[24:27], v[6:7], off offset:2064
	s_waitcnt vmcnt(21)
	v_lshlrev_b32_e32 v112, 16, v28
	v_and_b32_e32 v113, 0xffff0000, v28
	v_lshlrev_b32_e32 v114, 16, v29
	v_and_b32_e32 v115, 0xffff0000, v29
	v_lshlrev_b32_e32 v116, 16, v30
	v_and_b32_e32 v117, 0xffff0000, v30
	v_lshlrev_b32_e32 v118, 16, v31
	v_and_b32_e32 v119, 0xffff0000, v31
	v_mfma_f32_16x16x4_f32 v[8:11], v112, v32, v[8:11]
	v_mfma_f32_16x16x4_f32 v[8:11], v113, v33, v[8:11]
	v_mfma_f32_16x16x4_f32 v[8:11], v114, v34, v[8:11]
	v_mfma_f32_16x16x4_f32 v[8:11], v115, v35, v[8:11]
	v_mfma_f32_16x16x4_f32 v[8:11], v116, v36, v[8:11]
	v_mfma_f32_16x16x4_f32 v[8:11], v117, v37, v[8:11]
	v_mfma_f32_16x16x4_f32 v[8:11], v118, v38, v[8:11]
	v_mfma_f32_16x16x4_f32 v[8:11], v119, v39, v[8:11]
	global_load_dwordx4 v[28:31], v[4:5], off offset:1088
	global_load_dwordx4 v[32:35], v[6:7], off offset:2176
	global_load_dwordx4 v[36:39], v[6:7], off offset:2192
	s_waitcnt vmcnt(21)
	v_lshlrev_b32_e32 v112, 16, v40
	v_and_b32_e32 v113, 0xffff0000, v40
	v_lshlrev_b32_e32 v114, 16, v41
	v_and_b32_e32 v115, 0xffff0000, v41
	v_lshlrev_b32_e32 v116, 16, v42
	v_and_b32_e32 v117, 0xffff0000, v42
	v_lshlrev_b32_e32 v118, 16, v43
	v_and_b32_e32 v119, 0xffff0000, v43
	v_mfma_f32_16x16x4_f32 v[8:11], v112, v44, v[8:11]
	v_mfma_f32_16x16x4_f32 v[8:11], v113, v45, v[8:11]
	v_mfma_f32_16x16x4_f32 v[8:11], v114, v46, v[8:11]
	v_mfma_f32_16x16x4_f32 v[8:11], v115, v47, v[8:11]
	v_mfma_f32_16x16x4_f32 v[8:11], v116, v48, v[8:11]
	v_mfma_f32_16x16x4_f32 v[8:11], v117, v49, v[8:11]
	v_mfma_f32_16x16x4_f32 v[8:11], v118, v50, v[8:11]
	v_mfma_f32_16x16x4_f32 v[8:11], v119, v51, v[8:11]
	global_load_dwordx4 v[40:43], v[4:5], off offset:1152
	global_load_dwordx4 v[44:47], v[6:7], off offset:2304
	global_load_dwordx4 v[48:51], v[6:7], off offset:2320
	s_waitcnt vmcnt(21)
	v_lshlrev_b32_e32 v112, 16, v52
	v_and_b32_e32 v113, 0xffff0000, v52
	v_lshlrev_b32_e32 v114, 16, v53
	v_and_b32_e32 v115, 0xffff0000, v53
	v_lshlrev_b32_e32 v116, 16, v54
	v_and_b32_e32 v117, 0xffff0000, v54
	v_lshlrev_b32_e32 v118, 16, v55
	v_and_b32_e32 v119, 0xffff0000, v55
	v_mfma_f32_16x16x4_f32 v[8:11], v112, v56, v[8:11]
	v_mfma_f32_16x16x4_f32 v[8:11], v113, v57, v[8:11]
	v_mfma_f32_16x16x4_f32 v[8:11], v114, v58, v[8:11]
	v_mfma_f32_16x16x4_f32 v[8:11], v115, v59, v[8:11]
	v_mfma_f32_16x16x4_f32 v[8:11], v116, v60, v[8:11]
	v_mfma_f32_16x16x4_f32 v[8:11], v117, v61, v[8:11]
	v_mfma_f32_16x16x4_f32 v[8:11], v118, v62, v[8:11]
	v_mfma_f32_16x16x4_f32 v[8:11], v119, v63, v[8:11]
	global_load_dwordx4 v[52:55], v[4:5], off offset:1216
	global_load_dwordx4 v[56:59], v[6:7], off offset:2432
	global_load_dwordx4 v[60:63], v[6:7], off offset:2448
	s_waitcnt vmcnt(21)
	v_lshlrev_b32_e32 v112, 16, v64
	v_and_b32_e32 v113, 0xffff0000, v64
	v_lshlrev_b32_e32 v114, 16, v65
	v_and_b32_e32 v115, 0xffff0000, v65
	v_lshlrev_b32_e32 v116, 16, v66
	v_and_b32_e32 v117, 0xffff0000, v66
	v_lshlrev_b32_e32 v118, 16, v67
	v_and_b32_e32 v119, 0xffff0000, v67
	v_mfma_f32_16x16x4_f32 v[8:11], v112, v68, v[8:11]
	v_mfma_f32_16x16x4_f32 v[8:11], v113, v69, v[8:11]
	v_mfma_f32_16x16x4_f32 v[8:11], v114, v70, v[8:11]
	v_mfma_f32_16x16x4_f32 v[8:11], v115, v71, v[8:11]
	v_mfma_f32_16x16x4_f32 v[8:11], v116, v72, v[8:11]
	v_mfma_f32_16x16x4_f32 v[8:11], v117, v73, v[8:11]
	v_mfma_f32_16x16x4_f32 v[8:11], v118, v74, v[8:11]
	v_mfma_f32_16x16x4_f32 v[8:11], v119, v75, v[8:11]
	global_load_dwordx4 v[64:67], v[4:5], off offset:1280
	global_load_dwordx4 v[68:71], v[6:7], off offset:2560
	global_load_dwordx4 v[72:75], v[6:7], off offset:2576
	s_waitcnt vmcnt(21)
	v_lshlrev_b32_e32 v112, 16, v76
	v_and_b32_e32 v113, 0xffff0000, v76
	v_lshlrev_b32_e32 v114, 16, v77
	v_and_b32_e32 v115, 0xffff0000, v77
	v_lshlrev_b32_e32 v116, 16, v78
	v_and_b32_e32 v117, 0xffff0000, v78
	v_lshlrev_b32_e32 v118, 16, v79
	v_and_b32_e32 v119, 0xffff0000, v79
	v_mfma_f32_16x16x4_f32 v[8:11], v112, v80, v[8:11]
	v_mfma_f32_16x16x4_f32 v[8:11], v113, v81, v[8:11]
	v_mfma_f32_16x16x4_f32 v[8:11], v114, v82, v[8:11]
	v_mfma_f32_16x16x4_f32 v[8:11], v115, v83, v[8:11]
	v_mfma_f32_16x16x4_f32 v[8:11], v116, v84, v[8:11]
	v_mfma_f32_16x16x4_f32 v[8:11], v117, v85, v[8:11]
	v_mfma_f32_16x16x4_f32 v[8:11], v118, v86, v[8:11]
	v_mfma_f32_16x16x4_f32 v[8:11], v119, v87, v[8:11]
	global_load_dwordx4 v[76:79], v[4:5], off offset:1344
	global_load_dwordx4 v[80:83], v[6:7], off offset:2688
	global_load_dwordx4 v[84:87], v[6:7], off offset:2704
	s_waitcnt vmcnt(21)
; #define SHX(v, m) shx_((v), (m), lane)
; __device__ void ba_item(const Params& p, int L, int rp) {
;     ...
;       _Pragma("unroll") for (int j = 0; j < 8; ++j) {
;         float s = 0.f;
;         _Pragma("unroll") for (int e4 = 0; e4 < 4; ++e4) _Pragma("unroll") for (int e = 0; e < 4; ++e) s += hf[e4 * 4 + e] * wr_[j][e4][e];
;         _Pragma("unroll") for (int o = 32; o >= 1; o >>= 1) s += SHX(s, o);
	v_lshlrev_b32_e32 v112, 16, v88
	v_and_b32_e32 v113, 0xffff0000, v88
	v_lshlrev_b32_e32 v114, 16, v89
	v_and_b32_e32 v115, 0xffff0000, v89
	v_lshlrev_b32_e32 v116, 16, v90
	v_and_b32_e32 v117, 0xffff0000, v90
	v_lshlrev_b32_e32 v118, 16, v91
	v_and_b32_e32 v119, 0xffff0000, v91
	v_mfma_f32_16x16x4_f32 v[8:11], v112, v92, v[8:11]
	v_mfma_f32_16x16x4_f32 v[8:11], v113, v93, v[8:11]
	v_mfma_f32_16x16x4_f32 v[8:11], v114, v94, v[8:11]
	v_mfma_f32_16x16x4_f32 v[8:11], v115, v95, v[8:11]
	v_mfma_f32_16x16x4_f32 v[8:11], v116, v96, v[8:11]
	v_mfma_f32_16x16x4_f32 v[8:11], v117, v97, v[8:11]
	v_mfma_f32_16x16x4_f32 v[8:11], v118, v98, v[8:11]
	v_mfma_f32_16x16x4_f32 v[8:11], v119, v99, v[8:11]
	global_load_dwordx4 v[88:91], v[4:5], off offset:1408
	global_load_dwordx4 v[92:95], v[6:7], off offset:2816
	global_load_dwordx4 v[96:99], v[6:7], off offset:2832
	s_waitcnt vmcnt(21)
	v_lshlrev_b32_e32 v112, 16, v100
	v_and_b32_e32 v113, 0xffff0000, v100
	v_lshlrev_b32_e32 v114, 16, v101
	v_and_b32_e32 v115, 0xffff0000, v101
	v_lshlrev_b32_e32 v116, 16, v102
	v_and_b32_e32 v117, 0xffff0000, v102
	v_lshlrev_b32_e32 v118, 16, v103
	v_and_b32_e32 v119, 0xffff0000, v103
	v_mfma_f32_16x16x4_f32 v[8:11], v112, v104, v[8:11]
	v_mfma_f32_16x16x4_f32 v[8:11], v113, v105, v[8:11]
	v_mfma_f32_16x16x4_f32 v[8:11], v114, v106, v[8:11]
	v_mfma_f32_16x16x4_f32 v[8:11], v115, v107, v[8:11]
	v_mfma_f32_16x16x4_f32 v[8:11], v116, v108, v[8:11]
	v_mfma_f32_16x16x4_f32 v[8:11], v117, v109, v[8:11]
	v_mfma_f32_16x16x4_f32 v[8:11], v118, v110, v[8:11]
	v_mfma_f32_16x16x4_f32 v[8:11], v119, v111, v[8:11]
	global_load_dwordx4 v[100:103], v[4:5], off offset:1472
	global_load_dwordx4 v[104:107], v[6:7], off offset:2944
	global_load_dwordx4 v[108:111], v[6:7], off offset:2960
	s_waitcnt vmcnt(21)
	v_lshlrev_b32_e32 v112, 16, v16
	v_and_b32_e32 v113, 0xffff0000, v16
	v_lshlrev_b32_e32 v114, 16, v17
	v_and_b32_e32 v115, 0xffff0000, v17
	v_lshlrev_b32_e32 v116, 16, v18
	v_and_b32_e32 v117, 0xffff0000, v18
	v_lshlrev_b32_e32 v118, 16, v19
	v_and_b32_e32 v119, 0xffff0000, v19
	v_mfma_f32_16x16x4_f32 v[8:11], v112, v20, v[8:11]
	v_mfma_f32_16x16x4_f32 v[8:11], v113, v21, v[8:11]
	v_mfma_f32_16x16x4_f32 v[8:11], v114, v22, v[8:11]
	v_mfma_f32_16x16x4_f32 v[8:11], v115, v23, v[8:11]
	v_mfma_f32_16x16x4_f32 v[8:11], v116, v24, v[8:11]
	v_mfma_f32_16x16x4_f32 v[8:11], v117, v25, v[8:11]
	v_mfma_f32_16x16x4_f32 v[8:11], v118, v26, v[8:11]
	v_mfma_f32_16x16x4_f32 v[8:11], v119, v27, v[8:11]
	global_load_dwordx4 v[16:19], v[4:5], off offset:1536
	global_load_dwordx4 v[20:23], v[6:7], off offset:3072
	global_load_dwordx4 v[24:27], v[6:7], off offset:3088
	s_waitcnt vmcnt(21)
	v_lshlrev_b32_e32 v112, 16, v28
	v_and_b32_e32 v113, 0xffff0000, v28
	v_lshlrev_b32_e32 v114, 16, v29
	v_and_b32_e32 v115, 0xffff0000, v29
	v_lshlrev_b32_e32 v116, 16, v30
	v_and_b32_e32 v117, 0xffff0000, v30
	v_lshlrev_b32_e32 v118, 16, v31
	v_and_b32_e32 v119, 0xffff0000, v31
	v_mfma_f32_16x16x4_f32 v[8:11], v112, v32, v[8:11]
	v_mfma_f32_16x16x4_f32 v[8:11], v113, v33, v[8:11]
	v_mfma_f32_16x16x4_f32 v[8:11], v114, v34, v[8:11]
	v_mfma_f32_16x16x4_f32 v[8:11], v115, v35, v[8:11]
	v_mfma_f32_16x16x4_f32 v[8:11], v116, v36, v[8:11]
	v_mfma_f32_16x16x4_f32 v[8:11], v117, v37, v[8:11]
	v_mfma_f32_16x16x4_f32 v[8:11], v118, v38, v[8:11]
	v_mfma_f32_16x16x4_f32 v[8:11], v119, v39, v[8:11]
	global_load_dwordx4 v[28:31], v[4:5], off offset:1600
	global_load_dwordx4 v[32:35], v[6:7], off offset:3200
	global_load_dwordx4 v[36:39], v[6:7], off offset:3216
	s_waitcnt vmcnt(21)
	v_lshlrev_b32_e32 v112, 16, v40
	v_and_b32_e32 v113, 0xffff0000, v40
	v_lshlrev_b32_e32 v114, 16, v41
	v_and_b32_e32 v115, 0xffff0000, v41
	v_lshlrev_b32_e32 v116, 16, v42
	v_and_b32_e32 v117, 0xffff0000, v42
	v_lshlrev_b32_e32 v118, 16, v43
	v_and_b32_e32 v119, 0xffff0000, v43
	v_mfma_f32_16x16x4_f32 v[8:11], v112, v44, v[8:11]
	v_mfma_f32_16x16x4_f32 v[8:11], v113, v45, v[8:11]
	v_mfma_f32_16x16x4_f32 v[8:11], v114, v46, v[8:11]
	v_mfma_f32_16x16x4_f32 v[8:11], v115, v47, v[8:11]
	v_mfma_f32_16x16x4_f32 v[8:11], v116, v48, v[8:11]
	v_mfma_f32_16x16x4_f32 v[8:11], v117, v49, v[8:11]
	v_mfma_f32_16x16x4_f32 v[8:11], v118, v50, v[8:11]
	v_mfma_f32_16x16x4_f32 v[8:11], v119, v51, v[8:11]
	global_load_dwordx4 v[40:43], v[4:5], off offset:1664
	global_load_dwordx4 v[44:47], v[6:7], off offset:3328
	global_load_dwordx4 v[48:51], v[6:7], off offset:3344
	s_waitcnt vmcnt(21)
	v_lshlrev_b32_e32 v112, 16, v52
	v_and_b32_e32 v113, 0xffff0000, v52
	v_lshlrev_b32_e32 v114, 16, v53
	v_and_b32_e32 v115, 0xffff0000, v53
	v_lshlrev_b32_e32 v116, 16, v54
	v_and_b32_e32 v117, 0xffff0000, v54
	v_lshlrev_b32_e32 v118, 16, v55
	v_and_b32_e32 v119, 0xffff0000, v55
	v_mfma_f32_16x16x4_f32 v[8:11], v112, v56, v[8:11]
	v_mfma_f32_16x16x4_f32 v[8:11], v113, v57, v[8:11]
	v_mfma_f32_16x16x4_f32 v[8:11], v114, v58, v[8:11]
	v_mfma_f32_16x16x4_f32 v[8:11], v115, v59, v[8:11]
	v_mfma_f32_16x16x4_f32 v[8:11], v116, v60, v[8:11]
	v_mfma_f32_16x16x4_f32 v[8:11], v117, v61, v[8:11]
	v_mfma_f32_16x16x4_f32 v[8:11], v118, v62, v[8:11]
	v_mfma_f32_16x16x4_f32 v[8:11], v119, v63, v[8:11]
	global_load_dwordx4 v[52:55], v[4:5], off offset:1728
	global_load_dwordx4 v[56:59], v[6:7], off offset:3456
	global_load_dwordx4 v[60:63], v[6:7], off offset:3472
	s_waitcnt vmcnt(21)
; #define SHX(v, m) shx_((v), (m), lane)
; __device__ void ba_item(const Params& p, int L, int rp) {
;     ...
;       _Pragma("unroll") for (int j = 0; j < 8; ++j) {
;         float s = 0.f;
;         _Pragma("unroll") for (int e4 = 0; e4 < 4; ++e4) _Pragma("unroll") for (int e = 0; e < 4; ++e) s += hf[e4 * 4 + e] * wr_[j][e4][e];
;         _Pragma("unroll") for (int o = 32; o >= 1; o >>= 1) s += SHX(s, o);
	v_lshlrev_b32_e32 v112, 16, v64
	v_and_b32_e32 v113, 0xffff0000, v64
	v_lshlrev_b32_e32 v114, 16, v65
	v_and_b32_e32 v115, 0xffff0000, v65
	v_lshlrev_b32_e32 v116, 16, v66
	v_and_b32_e32 v117, 0xffff0000, v66
	v_lshlrev_b32_e32 v118, 16, v67
	v_and_b32_e32 v119, 0xffff0000, v67
	v_mfma_f32_16x16x4_f32 v[8:11], v112, v68, v[8:11]
	v_mfma_f32_16x16x4_f32 v[8:11], v113, v69, v[8:11]
	v_mfma_f32_16x16x4_f32 v[8:11], v114, v70, v[8:11]
	v_mfma_f32_16x16x4_f32 v[8:11], v115, v71, v[8:11]
	v_mfma_f32_16x16x4_f32 v[8:11], v116, v72, v[8:11]
	v_mfma_f32_16x16x4_f32 v[8:11], v117, v73, v[8:11]
	v_mfma_f32_16x16x4_f32 v[8:11], v118, v74, v[8:11]
	v_mfma_f32_16x16x4_f32 v[8:11], v119, v75, v[8:11]
	global_load_dwordx4 v[64:67], v[4:5], off offset:1792
	global_load_dwordx4 v[68:71], v[6:7], off offset:3584
	global_load_dwordx4 v[72:75], v[6:7], off offset:3600
	s_waitcnt vmcnt(21)
	v_lshlrev_b32_e32 v112, 16, v76
	v_and_b32_e32 v113, 0xffff0000, v76
	v_lshlrev_b32_e32 v114, 16, v77
	v_and_b32_e32 v115, 0xffff0000, v77
	v_lshlrev_b32_e32 v116, 16, v78
	v_and_b32_e32 v117, 0xffff0000, v78
	v_lshlrev_b32_e32 v118, 16, v79
	v_and_b32_e32 v119, 0xffff0000, v79
	v_mfma_f32_16x16x4_f32 v[8:11], v112, v80, v[8:11]
	v_mfma_f32_16x16x4_f32 v[8:11], v113, v81, v[8:11]
	v_mfma_f32_16x16x4_f32 v[8:11], v114, v82, v[8:11]
	v_mfma_f32_16x16x4_f32 v[8:11], v115, v83, v[8:11]
	v_mfma_f32_16x16x4_f32 v[8:11], v116, v84, v[8:11]
	v_mfma_f32_16x16x4_f32 v[8:11], v117, v85, v[8:11]
	v_mfma_f32_16x16x4_f32 v[8:11], v118, v86, v[8:11]
	v_mfma_f32_16x16x4_f32 v[8:11], v119, v87, v[8:11]
	global_load_dwordx4 v[76:79], v[4:5], off offset:1856
	global_load_dwordx4 v[80:83], v[6:7], off offset:3712
	global_load_dwordx4 v[84:87], v[6:7], off offset:3728
	s_waitcnt vmcnt(21)
	v_lshlrev_b32_e32 v112, 16, v88
	v_and_b32_e32 v113, 0xffff0000, v88
	v_lshlrev_b32_e32 v114, 16, v89
	v_and_b32_e32 v115, 0xffff0000, v89
	v_lshlrev_b32_e32 v116, 16, v90
	v_and_b32_e32 v117, 0xffff0000, v90
	v_lshlrev_b32_e32 v118, 16, v91
	v_and_b32_e32 v119, 0xffff0000, v91
	v_mfma_f32_16x16x4_f32 v[8:11], v112, v92, v[8:11]
	v_mfma_f32_16x16x4_f32 v[8:11], v113, v93, v[8:11]
	v_mfma_f32_16x16x4_f32 v[8:11], v114, v94, v[8:11]
	v_mfma_f32_16x16x4_f32 v[8:11], v115, v95, v[8:11]
	v_mfma_f32_16x16x4_f32 v[8:11], v116, v96, v[8:11]
	v_mfma_f32_16x16x4_f32 v[8:11], v117, v97, v[8:11]
	v_mfma_f32_16x16x4_f32 v[8:11], v118, v98, v[8:11]
	v_mfma_f32_16x16x4_f32 v[8:11], v119, v99, v[8:11]
	global_load_dwordx4 v[88:91], v[4:5], off offset:1920
	global_load_dwordx4 v[92:95], v[6:7], off offset:3840
	global_load_dwordx4 v[96:99], v[6:7], off offset:3856
	s_waitcnt vmcnt(21)
	v_lshlrev_b32_e32 v112, 16, v100
	v_and_b32_e32 v113, 0xffff0000, v100
	v_lshlrev_b32_e32 v114, 16, v101
	v_and_b32_e32 v115, 0xffff0000, v101
	v_lshlrev_b32_e32 v116, 16, v102
	v_and_b32_e32 v117, 0xffff0000, v102
	v_lshlrev_b32_e32 v118, 16, v103
	v_and_b32_e32 v119, 0xffff0000, v103
	v_mfma_f32_16x16x4_f32 v[8:11], v112, v104, v[8:11]
	v_mfma_f32_16x16x4_f32 v[8:11], v113, v105, v[8:11]
	v_mfma_f32_16x16x4_f32 v[8:11], v114, v106, v[8:11]
	v_mfma_f32_16x16x4_f32 v[8:11], v115, v107, v[8:11]
	v_mfma_f32_16x16x4_f32 v[8:11], v116, v108, v[8:11]
	v_mfma_f32_16x16x4_f32 v[8:11], v117, v109, v[8:11]
	v_mfma_f32_16x16x4_f32 v[8:11], v118, v110, v[8:11]
	v_mfma_f32_16x16x4_f32 v[8:11], v119, v111, v[8:11]
	global_load_dwordx4 v[100:103], v[4:5], off offset:1984
	global_load_dwordx4 v[104:107], v[6:7], off offset:3968
	global_load_dwordx4 v[108:111], v[6:7], off offset:3984
	s_waitcnt vmcnt(21)
	v_lshlrev_b32_e32 v112, 16, v16
	v_and_b32_e32 v113, 0xffff0000, v16
	v_lshlrev_b32_e32 v114, 16, v17
	v_and_b32_e32 v115, 0xffff0000, v17
	v_lshlrev_b32_e32 v116, 16, v18
	v_and_b32_e32 v117, 0xffff0000, v18
	v_lshlrev_b32_e32 v118, 16, v19
	v_and_b32_e32 v119, 0xffff0000, v19
	v_mfma_f32_16x16x4_f32 v[8:11], v112, v20, v[8:11]
	v_mfma_f32_16x16x4_f32 v[8:11], v113, v21, v[8:11]
	v_mfma_f32_16x16x4_f32 v[8:11], v114, v22, v[8:11]
	v_mfma_f32_16x16x4_f32 v[8:11], v115, v23, v[8:11]
	v_mfma_f32_16x16x4_f32 v[8:11], v116, v24, v[8:11]
	v_mfma_f32_16x16x4_f32 v[8:11], v117, v25, v[8:11]
	v_mfma_f32_16x16x4_f32 v[8:11], v118, v26, v[8:11]
	v_mfma_f32_16x16x4_f32 v[8:11], v119, v27, v[8:11]
	s_waitcnt vmcnt(18)
	v_lshlrev_b32_e32 v112, 16, v28
	v_and_b32_e32 v113, 0xffff0000, v28
	v_lshlrev_b32_e32 v114, 16, v29
	v_and_b32_e32 v115, 0xffff0000, v29
	v_lshlrev_b32_e32 v116, 16, v30
	v_and_b32_e32 v117, 0xffff0000, v30
	v_lshlrev_b32_e32 v118, 16, v31
	v_and_b32_e32 v119, 0xffff0000, v31
	v_mfma_f32_16x16x4_f32 v[8:11], v112, v32, v[8:11]
	v_mfma_f32_16x16x4_f32 v[8:11], v113, v33, v[8:11]
	v_mfma_f32_16x16x4_f32 v[8:11], v114, v34, v[8:11]
	v_mfma_f32_16x16x4_f32 v[8:11], v115, v35, v[8:11]
	v_mfma_f32_16x16x4_f32 v[8:11], v116, v36, v[8:11]
	v_mfma_f32_16x16x4_f32 v[8:11], v117, v37, v[8:11]
	v_mfma_f32_16x16x4_f32 v[8:11], v118, v38, v[8:11]
	v_mfma_f32_16x16x4_f32 v[8:11], v119, v39, v[8:11]
	s_waitcnt vmcnt(15)
	v_lshlrev_b32_e32 v112, 16, v40
	v_and_b32_e32 v113, 0xffff0000, v40
	v_lshlrev_b32_e32 v114, 16, v41
	v_and_b32_e32 v115, 0xffff0000, v41
	v_lshlrev_b32_e32 v116, 16, v42
	v_and_b32_e32 v117, 0xffff0000, v42
	v_lshlrev_b32_e32 v118, 16, v43
	v_and_b32_e32 v119, 0xffff0000, v43
	v_mfma_f32_16x16x4_f32 v[8:11], v112, v44, v[8:11]
	v_mfma_f32_16x16x4_f32 v[8:11], v113, v45, v[8:11]
	v_mfma_f32_16x16x4_f32 v[8:11], v114, v46, v[8:11]
	v_mfma_f32_16x16x4_f32 v[8:11], v115, v47, v[8:11]
	v_mfma_f32_16x16x4_f32 v[8:11], v116, v48, v[8:11]
	v_mfma_f32_16x16x4_f32 v[8:11], v117, v49, v[8:11]
	v_mfma_f32_16x16x4_f32 v[8:11], v118, v50, v[8:11]
	v_mfma_f32_16x16x4_f32 v[8:11], v119, v51, v[8:11]
	s_waitcnt vmcnt(12)
; #define SHX(v, m) shx_((v), (m), lane)
; __device__ void ba_item(const Params& p, int L, int rp) {
;     ...
;       _Pragma("unroll") for (int j = 0; j < 8; ++j) {
;         float s = 0.f;
;         _Pragma("unroll") for (int e4 = 0; e4 < 4; ++e4) _Pragma("unroll") for (int e = 0; e < 4; ++e) s += hf[e4 * 4 + e] * wr_[j][e4][e];
;         _Pragma("unroll") for (int o = 32; o >= 1; o >>= 1) s += SHX(s, o);
	v_lshlrev_b32_e32 v112, 16, v52
	v_and_b32_e32 v113, 0xffff0000, v52
	v_lshlrev_b32_e32 v114, 16, v53
	v_and_b32_e32 v115, 0xffff0000, v53
	v_lshlrev_b32_e32 v116, 16, v54
	v_and_b32_e32 v117, 0xffff0000, v54
	v_lshlrev_b32_e32 v118, 16, v55
	v_and_b32_e32 v119, 0xffff0000, v55
	v_mfma_f32_16x16x4_f32 v[8:11], v112, v56, v[8:11]
	v_mfma_f32_16x16x4_f32 v[8:11], v113, v57, v[8:11]
	v_mfma_f32_16x16x4_f32 v[8:11], v114, v58, v[8:11]
	v_mfma_f32_16x16x4_f32 v[8:11], v115, v59, v[8:11]
	v_mfma_f32_16x16x4_f32 v[8:11], v116, v60, v[8:11]
	v_mfma_f32_16x16x4_f32 v[8:11], v117, v61, v[8:11]
	v_mfma_f32_16x16x4_f32 v[8:11], v118, v62, v[8:11]
	v_mfma_f32_16x16x4_f32 v[8:11], v119, v63, v[8:11]
	s_waitcnt vmcnt(9)
	v_lshlrev_b32_e32 v112, 16, v64
	v_and_b32_e32 v113, 0xffff0000, v64
	v_lshlrev_b32_e32 v114, 16, v65
	v_and_b32_e32 v115, 0xffff0000, v65
	v_lshlrev_b32_e32 v116, 16, v66
	v_and_b32_e32 v117, 0xffff0000, v66
	v_lshlrev_b32_e32 v118, 16, v67
	v_and_b32_e32 v119, 0xffff0000, v67
	v_mfma_f32_16x16x4_f32 v[8:11], v112, v68, v[8:11]
	v_mfma_f32_16x16x4_f32 v[8:11], v113, v69, v[8:11]
	v_mfma_f32_16x16x4_f32 v[8:11], v114, v70, v[8:11]
	v_mfma_f32_16x16x4_f32 v[8:11], v115, v71, v[8:11]
	v_mfma_f32_16x16x4_f32 v[8:11], v116, v72, v[8:11]
	v_mfma_f32_16x16x4_f32 v[8:11], v117, v73, v[8:11]
	v_mfma_f32_16x16x4_f32 v[8:11], v118, v74, v[8:11]
	v_mfma_f32_16x16x4_f32 v[8:11], v119, v75, v[8:11]
	s_waitcnt vmcnt(6)
	v_lshlrev_b32_e32 v112, 16, v76
	v_and_b32_e32 v113, 0xffff0000, v76
	v_lshlrev_b32_e32 v114, 16, v77
	v_and_b32_e32 v115, 0xffff0000, v77
	v_lshlrev_b32_e32 v116, 16, v78
	v_and_b32_e32 v117, 0xffff0000, v78
	v_lshlrev_b32_e32 v118, 16, v79
	v_and_b32_e32 v119, 0xffff0000, v79
	v_mfma_f32_16x16x4_f32 v[8:11], v112, v80, v[8:11]
	v_mfma_f32_16x16x4_f32 v[8:11], v113, v81, v[8:11]
	v_mfma_f32_16x16x4_f32 v[8:11], v114, v82, v[8:11]
	v_mfma_f32_16x16x4_f32 v[8:11], v115, v83, v[8:11]
	v_mfma_f32_16x16x4_f32 v[8:11], v116, v84, v[8:11]
	v_mfma_f32_16x16x4_f32 v[8:11], v117, v85, v[8:11]
	v_mfma_f32_16x16x4_f32 v[8:11], v118, v86, v[8:11]
	v_mfma_f32_16x16x4_f32 v[8:11], v119, v87, v[8:11]
	s_waitcnt vmcnt(3)
	v_lshlrev_b32_e32 v112, 16, v88
	v_and_b32_e32 v113, 0xffff0000, v88
	v_lshlrev_b32_e32 v114, 16, v89
	v_and_b32_e32 v115, 0xffff0000, v89
	v_lshlrev_b32_e32 v116, 16, v90
	v_and_b32_e32 v117, 0xffff0000, v90
	v_lshlrev_b32_e32 v118, 16, v91
	v_and_b32_e32 v119, 0xffff0000, v91
	v_mfma_f32_16x16x4_f32 v[8:11], v112, v92, v[8:11]
	v_mfma_f32_16x16x4_f32 v[8:11], v113, v93, v[8:11]
	v_mfma_f32_16x16x4_f32 v[8:11], v114, v94, v[8:11]
	v_mfma_f32_16x16x4_f32 v[8:11], v115, v95, v[8:11]
	v_mfma_f32_16x16x4_f32 v[8:11], v116, v96, v[8:11]
	v_mfma_f32_16x16x4_f32 v[8:11], v117, v97, v[8:11]
	v_mfma_f32_16x16x4_f32 v[8:11], v118, v98, v[8:11]
	v_mfma_f32_16x16x4_f32 v[8:11], v119, v99, v[8:11]
	s_waitcnt vmcnt(0)
; __device__ __forceinline__ float fexp(float x) { return __builtin_amdgcn_exp2f(x * 1.4426950408889634f); }
; __device__ __forceinline__ float flog(float x) { return __builtin_amdgcn_logf(x) * 0.6931471805599453f; }
; __device__ __forceinline__ float frsq(float x) { return __builtin_amdgcn_rsqf(x); }
; __device__ __forceinline__ float sigmoidf_(float x) { return frcp(1.0f + fexp(-x)); }
; #define SHX(v, m) shx_((v), (m), lane)
; __device__ void ba_item(const Params& p, int L, int rp) {
;     ...
;       _Pragma("unroll") for (int j = 0; j < 8; ++j) {
;         float s = 0.f;
;         _Pragma("unroll") for (int e4 = 0; e4 < 4; ++e4) _Pragma("unroll") for (int e = 0; e < 4; ++e) s += hf[e4 * 4 + e] * wr_[j][e4][e];
;         _Pragma("unroll") for (int o = 32; o >= 1; o >>= 1) s += SHX(s, o);
;         a[j] = s;
;       }
;       if (lane < 8) {
;         float s16 = 0.f;
;         _Pragma("unroll") for (int i = 0; i < 4; ++i) s16 += (ps[u][i][0] + ps[u][i][1]) + (ps[u][i][2] + ps[u][i][3]);
;         float rs = frsq(s16 * (1.0f / 1024.0f) + 1e-6f);
;         float v = 0.f;
;         _Pragma("unroll") for (int j = 0; j < 8; ++j) if (lane == j) v = a[j];
;         v *= rs;
;         float r;
;         if (lane < 4) r = sigmoidf_(v);
;         else {
;           int hh = lane - 4;
;           float z = v + p.dn_dt_bias[(L >> 1) * 4 + hh];
;           float sp = (z > 20.f) ? z : flog(1.0f + fexp(z));
;           r = -fexp(p.dn_a_log[(L >> 1) * 4 + hh]) * sp;
;         }
;         miscw[MF_BG + (long)row * 8 + lane] = r;
;       }
	v_lshlrev_b32_e32 v112, 16, v100
	v_and_b32_e32 v113, 0xffff0000, v100
	v_lshlrev_b32_e32 v114, 16, v101
	v_and_b32_e32 v115, 0xffff0000, v101
	v_lshlrev_b32_e32 v116, 16, v102
	v_and_b32_e32 v117, 0xffff0000, v102
	v_lshlrev_b32_e32 v118, 16, v103
	v_and_b32_e32 v119, 0xffff0000, v103
	v_mfma_f32_16x16x4_f32 v[8:11], v112, v104, v[8:11]
	v_mfma_f32_16x16x4_f32 v[8:11], v113, v105, v[8:11]
	v_mfma_f32_16x16x4_f32 v[8:11], v114, v106, v[8:11]
	v_mfma_f32_16x16x4_f32 v[8:11], v115, v107, v[8:11]
	v_mfma_f32_16x16x4_f32 v[8:11], v116, v108, v[8:11]
	v_mfma_f32_16x16x4_f32 v[8:11], v117, v109, v[8:11]
	v_mfma_f32_16x16x4_f32 v[8:11], v118, v110, v[8:11]
	v_mfma_f32_16x16x4_f32 v[8:11], v119, v111, v[8:11]
	v_cmp_gt_u32_e32 vcc, 8, v2
	s_and_saveexec_b64 s[12:13], vcc
	s_nop 4
	v_add_f32_e32 v120, v120, v121
	v_add_f32_e32 v122, v122, v123
	v_add_f32_e32 v120, v120, v122
	v_add_f32_e32 v124, v124, v125
	v_add_f32_e32 v126, v126, v127
	v_add_f32_e32 v124, v124, v126
	v_add_f32_e32 v128, v128, v129
	v_add_f32_e32 v130, v130, v131
	v_add_f32_e32 v128, v128, v130
	v_add_f32_e32 v132, v132, v133
	v_add_f32_e32 v134, v134, v135
	v_add_f32_e32 v132, v132, v134
	v_add_f32_e32 v120, 0, v120
	v_add_f32_e32 v120, v124, v120
	v_add_f32_e32 v120, v128, v120
	v_add_f32_e32 v120, v132, v120
	v_fmamk_f32 v120, v120, 0x3a800000, v201
	v_rsq_f32_e32 v120, v120
	s_nop 0
	v_mul_f32_e32 v192, v8, v120
	v_mul_f32_e32 v193, 0xbfb8aa3b, v192
	v_exp_f32_e32 v193, v193
	s_nop 0
	v_add_f32_e32 v193, 1.0, v193
	v_rcp_f32_e32 v193, v193
	v_add_f32_e32 v194, v192, v190
	v_mul_f32_e32 v195, 0x3fb8aa3b, v194
	v_exp_f32_e32 v195, v195
	v_cmp_lt_f32_e64 s[0:1], s57, v194
	v_add_f32_e32 v195, 1.0, v195
	v_log_f32_e32 v195, v195
	s_nop 0
	v_mul_f32_e32 v195, 0x3f317218, v195
	v_cndmask_b32_e64 v194, v195, v194, s[0:1]
	v_mul_f32_e32 v195, 0x3fb8aa3b, v191
	v_exp_f32_e32 v195, v195
	s_nop 0
	v_mul_f32_e64 v194, v194, -v195
	v_cmp_gt_u32_e64 s[0:1], 4, v186
	s_nop 1
	v_cndmask_b32_e64 v194, v194, v193, s[0:1]
	global_store_dword v[188:189], v194, off offset:0
	v_add_f32_e32 v136, v136, v137
	v_add_f32_e32 v138, v138, v139
	v_add_f32_e32 v136, v136, v138
	v_add_f32_e32 v140, v140, v141
	v_add_f32_e32 v142, v142, v143
	v_add_f32_e32 v140, v140, v142
	v_add_f32_e32 v144, v144, v145
	v_add_f32_e32 v146, v146, v147
	v_add_f32_e32 v144, v144, v146
	v_add_f32_e32 v148, v148, v149
	v_add_f32_e32 v150, v150, v151
	v_add_f32_e32 v148, v148, v150
	v_add_f32_e32 v136, 0, v136
	v_add_f32_e32 v136, v140, v136
	v_add_f32_e32 v136, v144, v136
	v_add_f32_e32 v136, v148, v136
	v_fmamk_f32 v136, v136, 0x3a800000, v201
	v_rsq_f32_e32 v136, v136
	s_nop 0
	v_mul_f32_e32 v192, v9, v136
	v_mul_f32_e32 v193, 0xbfb8aa3b, v192
	v_exp_f32_e32 v193, v193
	s_nop 0
	v_add_f32_e32 v193, 1.0, v193
	v_rcp_f32_e32 v193, v193
	v_add_f32_e32 v194, v192, v190
	v_mul_f32_e32 v195, 0x3fb8aa3b, v194
	v_exp_f32_e32 v195, v195
	v_cmp_lt_f32_e64 s[0:1], s57, v194
	v_add_f32_e32 v195, 1.0, v195
	v_log_f32_e32 v195, v195
	s_nop 0
	v_mul_f32_e32 v195, 0x3f317218, v195
	v_cndmask_b32_e64 v194, v195, v194, s[0:1]
	v_mul_f32_e32 v195, 0x3fb8aa3b, v191
	v_exp_f32_e32 v195, v195
	s_nop 0
	v_mul_f32_e64 v194, v194, -v195
	v_cmp_gt_u32_e64 s[0:1], 4, v186
	s_nop 1
	v_cndmask_b32_e64 v194, v194, v193, s[0:1]
	global_store_dword v[188:189], v194, off offset:32
	v_add_f32_e32 v152, v152, v153
	v_add_f32_e32 v154, v154, v155
	v_add_f32_e32 v152, v152, v154
	v_add_f32_e32 v156, v156, v157
	v_add_f32_e32 v158, v158, v159
	v_add_f32_e32 v156, v156, v158
	v_add_f32_e32 v160, v160, v161
	v_add_f32_e32 v162, v162, v163
	v_add_f32_e32 v160, v160, v162
	v_add_f32_e32 v164, v164, v165
	v_add_f32_e32 v166, v166, v167
	v_add_f32_e32 v164, v164, v166
	v_add_f32_e32 v152, 0, v152
	v_add_f32_e32 v152, v156, v152
	v_add_f32_e32 v152, v160, v152
	v_add_f32_e32 v152, v164, v152
	v_fmamk_f32 v152, v152, 0x3a800000, v201
	v_rsq_f32_e32 v152, v152
	s_nop 0
	v_mul_f32_e32 v192, v10, v152
	v_mul_f32_e32 v193, 0xbfb8aa3b, v192
	v_exp_f32_e32 v193, v193
	s_nop 0
	v_add_f32_e32 v193, 1.0, v193
	v_rcp_f32_e32 v193, v193
	v_add_f32_e32 v194, v192, v190
	v_mul_f32_e32 v195, 0x3fb8aa3b, v194
	v_exp_f32_e32 v195, v195
	v_cmp_lt_f32_e64 s[0:1], s57, v194
	v_add_f32_e32 v195, 1.0, v195
	v_log_f32_e32 v195, v195
	s_nop 0
	v_mul_f32_e32 v195, 0x3f317218, v195
	v_cndmask_b32_e64 v194, v195, v194, s[0:1]
	v_mul_f32_e32 v195, 0x3fb8aa3b, v191
	v_exp_f32_e32 v195, v195
	s_nop 0
	v_mul_f32_e64 v194, v194, -v195
	v_cmp_gt_u32_e64 s[0:1], 4, v186
	s_nop 1
	v_cndmask_b32_e64 v194, v194, v193, s[0:1]
	global_store_dword v[188:189], v194, off offset:64
	v_add_f32_e32 v168, v168, v169
	v_add_f32_e32 v170, v170, v171
	v_add_f32_e32 v168, v168, v170
	v_add_f32_e32 v172, v172, v173
	v_add_f32_e32 v174, v174, v175
	v_add_f32_e32 v172, v172, v174
	v_add_f32_e32 v176, v176, v177
	v_add_f32_e32 v178, v178, v179
	v_add_f32_e32 v176, v176, v178
	v_add_f32_e32 v180, v180, v181
	v_add_f32_e32 v182, v182, v183
	v_add_f32_e32 v180, v180, v182
	v_add_f32_e32 v168, 0, v168
	v_add_f32_e32 v168, v172, v168
	v_add_f32_e32 v168, v176, v168
	v_add_f32_e32 v168, v180, v168
	v_fmamk_f32 v168, v168, 0x3a800000, v201
	v_rsq_f32_e32 v168, v168
	s_nop 0
	v_mul_f32_e32 v192, v11, v168
	v_mul_f32_e32 v193, 0xbfb8aa3b, v192
	v_exp_f32_e32 v193, v193
	s_nop 0
	v_add_f32_e32 v193, 1.0, v193
	v_rcp_f32_e32 v193, v193
	v_add_f32_e32 v194, v192, v190
	v_mul_f32_e32 v195, 0x3fb8aa3b, v194
	v_exp_f32_e32 v195, v195
	v_cmp_lt_f32_e64 s[0:1], s57, v194
	v_add_f32_e32 v195, 1.0, v195
	v_log_f32_e32 v195, v195
	s_nop 0
	v_mul_f32_e32 v195, 0x3f317218, v195
	v_cndmask_b32_e64 v194, v195, v194, s[0:1]
	v_mul_f32_e32 v195, 0x3fb8aa3b, v191
	v_exp_f32_e32 v195, v195
	s_nop 0
	v_mul_f32_e64 v194, v194, -v195
	v_cmp_gt_u32_e64 s[0:1], 4, v186
	s_nop 1
	v_cndmask_b32_e64 v194, v194, v193, s[0:1]
	global_store_dword v[188:189], v194, off offset:96
	s_or_b64 exec, exec, s[12:13]
	s_branch .LBB0_627
